# grid barrier: each workgroup issues its acquire-side buffer_inv right after its arrival (no cached loads until the barrier completes), overlapping it with the wait instead of paying it after the barri
# speedup vs baseline: 1.0098x; 1.0059x over previous
.LBB0_31:
	s_lshl_b32 s3, s3, 8
	s_add_u32 s10, s6, s3
	s_addc_u32 s11, s7, 0
	v_mov_b32_e32 v0, 0x23fc8
	ds_read2_b32 v[4:5], v0 offset1:1
	v_mov_b32_e32 v6, 1
	v_mov_b32_e32 v7, 0x1000
	global_atomic_add v7, v6, s[10:11] offset:1024
	s_waitcnt lgkmcnt(0)
	v_add_u32_e32 v8, 1, v5
	v_mov_b32_e32 v9, 0x23fcc
	ds_write_b32 v9, v8
	v_mul_lo_u32 v10, v8, v3
	v_mul_lo_u32 v11, v8, v2
	buffer_inv sc1
	v_cmp_ne_u32_e32 vcc, 0, v4
	s_cbranch_vccnz .Lnb_poll_top_r
	s_mov_b32 s3, 0

.Lnb_spin_top_r:
	global_load_dword v6, v12, s[6:7] sc1
	s_waitcnt vmcnt(0)
	v_cmp_le_u32_e32 vcc, v11, v6
	s_cbranch_vccnz .Lnb_done_r
	s_sleep 1
	s_add_i32 s3, s3, 1
	s_cmp_lt_u32 s3, 0x40000
	s_cbranch_scc1 .Lnb_spin_top_r
.Lnb_done_r:
	s_waitcnt vmcnt(0)
.LBB0_67:
	s_or_b64 exec, exec, s[4:5]
	s_mov_b64 s[4:5], 0
	s_waitcnt lgkmcnt(0)
	s_barrier

.LBB0_664:
	s_lshl_b32 s2, s2, 8
	s_add_u32 s10, s6, s2
	s_addc_u32 s11, s7, 0
	v_mov_b32_e32 v0, 0x23fc8
	ds_read2_b32 v[4:5], v0 offset1:1
	v_mov_b32_e32 v6, 1
	v_mov_b32_e32 v7, 0x1000
	global_atomic_add v7, v6, s[10:11] offset:1024
	s_waitcnt lgkmcnt(0)
	v_add_u32_e32 v8, 1, v5
	v_mov_b32_e32 v9, 0x23fcc
	ds_write_b32 v9, v8
	v_mul_lo_u32 v10, v8, v3
	v_mul_lo_u32 v11, v8, v2
	buffer_inv sc1
	v_cmp_ne_u32_e32 vcc, 0, v4
	s_cbranch_vccnz .Lnb_poll_top_m
	s_mov_b32 s2, 0

.Lnb_spin_top_m:
	global_load_dword v6, v12, s[6:7] sc1
	s_waitcnt vmcnt(0)
	v_cmp_le_u32_e32 vcc, v11, v6
	s_cbranch_vccnz .Lnb_done_m
	s_sleep 1
	s_add_i32 s2, s2, 1
	s_cmp_lt_u32 s2, 0x40000
	s_cbranch_scc1 .Lnb_spin_top_m
.Lnb_done_m:
	s_waitcnt vmcnt(0)
.LBB0_700:
	s_or_b64 exec, exec, s[4:5]
	s_waitcnt lgkmcnt(0)
	s_barrier
	s_mov_b64 s[4:5], 0
